# EVENA chunk-state operand fragments via ds_read_b64_tr_b16 (24 transpose reads instead of 96 u16 gathers) on top of the final stack
# speedup vs baseline: 1.0056x; 1.0018x over previous
.LBB0_462:
	s_cmpk_gt_i32 s4, 0x3ff
	s_cbranch_scc1 .LBB0_465
	v_ashrrev_i32_e32 v38, 3, v53
	v_and_b32_e32 v0, 56, v72
	v_sub_u32_e32 v2, 63, v38
	v_lshlrev_b32_e32 v168, 3, v0
	v_cvt_f32_i32_e32 v39, v2
	v_lshl_add_u64 v[2:3], s[10:11], 0, v[168:169]
	s_mov_b64 s[12:13], 0x100000
	s_ashr_i32 s5, s5, 6
	v_lshl_add_u64 v[32:33], v[2:3], 0, s[12:13]
	s_movk_i32 s12, 0x110
	v_mul_lo_u32 v2, v38, s12
	s_lshl_b32 s12, s5, 5
	v_lshlrev_b32_e32 v3, 1, v0
	s_and_b32 s13, s12, 0x60
	v_add3_u32 v40, 0, v2, v3
	s_lshl_b32 s5, s5, 4
	s_lshl_b32 s12, s13, 1
	v_lshlrev_b32_e32 v2, 1, v53
	s_and_b32 s14, s5, 0xffffffc0
	s_add_i32 s12, s12, 0
	v_and_b32_e32 v4, 62, v2
	v_add_u32_e32 v5, s12, v4
	s_lshl_b32 s12, s14, 1
	s_add_i32 s12, s12, 0
	v_bfi_b32 v2, 63, v53, s5
	s_ashr_i32 s15, s14, 31
	s_ashr_i32 s5, s4, 31
	v_bfe_u32 v1, v53, 5, 1
	v_add_u32_e32 v6, s12, v4
	s_lshl_b32 s12, s4, 4
	s_lshl_b64 s[16:17], s[4:5], 15
	s_lshl_b64 s[14:15], s[14:15], 1
	v_mul_u32_u24_e32 v8, 0x880, v1
	s_add_u32 s14, s16, s14
	v_lshlrev_b32_e32 v1, 10, v1
	v_lshl_or_b32 v2, v2, 1, 64
	s_addc_u32 s15, s17, s15
	v_lshl_or_b32 v168, s13, 8, v1
	v_add_u32_e32 v7, 0, v2
	v_lshl_add_u64 v[2:3], s[14:15], 0, v[168:169]
	v_or_b32_e32 v2, v2, v4
	v_lshl_add_u64 v[2:3], s[10:11], 0, v[2:3]
	s_mov_b64 s[10:11], 0x11701b40
	v_lshl_add_u64 v[34:35], v[2:3], 0, s[10:11]
	v_lshlrev_b32_e32 v168, 1, v0
	v_add_u32_e32 v41, v5, v8
	v_add_u32_e32 v42, v6, v8
	v_add_u32_e32 v43, v7, v8
	v_and_b32_e32 v152, 63, v53
	v_lshrrev_b32_e32 v153, 5, v152
	v_bfe_u32 v154, v152, 2, 2
	v_lshl_add_u32 v153, v153, 3, v154
	v_mul_u32_u24_e32 v153, 0x110, v153
	v_bfe_u32 v154, v152, 4, 1
	v_and_b32_e32 v155, 3, v152
	v_lshlrev_b32_e32 v154, 5, v154
	v_lshl_add_u32 v154, v155, 3, v154
	v_add_u32_e32 v153, v153, v154
	v_sub_u32_e32 v152, v5, v4
	v_sub_u32_e32 v155, v6, v4
	v_sub_u32_e32 v154, v7, v4
	v_add_u32_e32 v152, v152, v153
	v_add_u32_e32 v155, v155, v153
	v_add_u32_e32 v154, v154, v153
	v_and_b32_e32 v158, 1, v53
	v_mul_u32_u24_e32 v156, 0xfe, v158
	v_mov_b32_e32 v157, 0
	v_mov_b32_e32 v162, 0x5040100
	v_mov_b32_e32 v163, 0x3020706
	v_cmp_ne_u32_e32 vcc, 0, v158
	s_nop 1
	v_cndmask_b32_e32 v162, v162, v163, vcc
	s_and_b32 s13, s12, 0xfc0
	s_and_b32 s14, s12, 0xffffffc0
	s_and_b32 s26, s4, 3
	s_lshl_b32 s26, s26, 8
	v_mov_b64_e32 v[110:111], s[6:7]
	v_add_u32_e32 v113, s14, v38
	v_add_u32_e32 v112, s13, v38
	v_mad_i64_i32 v[110:111], s[14:15], v113, s85, v[110:111]
	v_ashrrev_i32_e32 v113, 31, v112
	v_lshl_add_u64 v[110:111], v[110:111], 0, s[26:27]
	v_lshlrev_b64 v[112:113], 9, v[112:113]
	v_lshl_add_u64 v[116:117], v[110:111], 0, v[168:169]
	v_lshl_add_u64 v[114:115], v[32:33], 0, v[112:113]
	s_mov_b64 s[14:15], 0x1000
	global_load_dwordx4 v[120:123], v[114:115], off
	global_load_dwordx4 v[124:127], v[114:115], off offset:16
	global_load_dwordx4 v[128:131], v[114:115], off offset:48
	global_load_dwordx4 v[132:135], v[114:115], off offset:32
	v_lshl_add_u64 v[118:119], v[116:117], 0, s[14:15]
	global_load_dwordx4 v[136:139], v[118:119], off
	global_load_dwordx4 v[140:143], v[118:119], off offset:128
	global_load_dwordx4 v[144:147], v[118:119], off offset:1024
	global_load_dwordx4 v[148:151], v[118:119], off offset:1152
	s_waitcnt vmcnt(0)

.Levena_nopf:
	s_waitcnt lgkmcnt(0)
	v_mul_f32_e32 v44, s5, v39
	v_exp_f32_e32 v44, v44
	s_nop 0
	v_mul_f32_e32 v44, 0x3db504f3, v44
	ds_write_b128 v40, v[24:27] offset:17408
	ds_write_b128 v40, v[28:31] offset:17536
	v_mov_b32_e32 v46, v0
	v_mov_b32_e32 v47, v2
	v_mov_b32_e32 v2, v1
	v_mov_b32_e32 v0, v4
	v_mov_b32_e32 v1, v6
	v_mov_b32_e32 v6, v5
	v_mov_b32_e32 v4, v12
	v_mov_b32_e32 v5, v14
	v_mov_b32_e32 v14, v13
	v_mov_b32_e32 v13, v10
	v_mov_b32_e32 v10, v9
	v_lshlrev_b32_e32 v48, 16, v20
	v_and_b32_e32 v49, 0xffff0000, v20
	v_lshlrev_b32_e32 v20, 16, v21
	v_and_b32_e32 v21, 0xffff0000, v21
	v_lshlrev_b32_e32 v52, 16, v22
	v_and_b32_e32 v53, 0xffff0000, v22
	v_lshlrev_b32_e32 v22, 16, v23
	v_and_b32_e32 v23, 0xffff0000, v23
	v_mov_b32_e32 v12, v8
	v_lshlrev_b32_e32 v8, 16, v16
	v_and_b32_e32 v9, 0xffff0000, v16
	v_lshlrev_b32_e32 v16, 16, v17
	v_and_b32_e32 v17, 0xffff0000, v17
	v_lshlrev_b32_e32 v50, 16, v18
	v_and_b32_e32 v51, 0xffff0000, v18
	v_lshlrev_b32_e32 v18, 16, v19
	v_and_b32_e32 v19, 0xffff0000, v19
	v_pk_mul_f32 v[24:25], v[2:3], v[48:49]
	v_pk_mul_f32 v[26:27], v[46:47], v[48:49]
	v_pk_mul_f32 v[28:29], v[6:7], v[20:21]
	v_pk_mul_f32 v[30:31], v[14:15], v[52:53]
	v_pk_mul_f32 v[48:49], v[4:5], v[52:53]
	v_pk_mul_f32 v[52:53], v[10:11], v[22:23]
	v_pk_mul_f32 v[20:21], v[0:1], v[20:21]
	v_pk_mul_f32 v[22:23], v[12:13], v[22:23]
	v_pk_fma_f32 v[24:25], v[46:47], v[8:9], v[24:25] neg_lo:[0,0,1] neg_hi:[0,0,1]
	v_pk_fma_f32 v[2:3], v[2:3], v[8:9], v[26:27]
	v_pk_fma_f32 v[0:1], v[0:1], v[16:17], v[28:29] neg_lo:[0,0,1] neg_hi:[0,0,1]
	v_pk_fma_f32 v[4:5], v[4:5], v[50:51], v[30:31] neg_lo:[0,0,1] neg_hi:[0,0,1]
	v_pk_fma_f32 v[12:13], v[12:13], v[18:19], v[52:53] neg_lo:[0,0,1] neg_hi:[0,0,1]
	v_pk_fma_f32 v[6:7], v[6:7], v[16:17], v[20:21]
	v_pk_fma_f32 v[8:9], v[14:15], v[50:51], v[48:49]
	v_pk_fma_f32 v[10:11], v[10:11], v[18:19], v[22:23]
	v_pk_mul_f32 v[14:15], v[44:45], v[24:25] op_sel_hi:[0,1]
	v_pk_mul_f32 v[2:3], v[44:45], v[2:3] op_sel_hi:[0,1]
	v_pk_mul_f32 v[16:17], v[44:45], v[0:1] op_sel_hi:[0,1]
	v_pk_mul_f32 v[18:19], v[44:45], v[4:5] op_sel_hi:[0,1]
	v_pk_mul_f32 v[12:13], v[44:45], v[12:13] op_sel_hi:[0,1]
	v_pk_mul_f32 v[6:7], v[44:45], v[6:7] op_sel_hi:[0,1]
	v_pk_mul_f32 v[8:9], v[44:45], v[8:9] op_sel_hi:[0,1]
	v_pk_mul_f32 v[10:11], v[44:45], v[10:11] op_sel_hi:[0,1]
	v_cvt_pk_bf16_f32 v0, v14, v15
	v_cvt_pk_bf16_f32 v4, v2, v3
	v_cvt_pk_bf16_f32 v1, v16, v17
	v_cvt_pk_bf16_f32 v2, v18, v19
	v_cvt_pk_bf16_f32 v3, v12, v13
	v_cvt_pk_bf16_f32 v5, v6, v7
	v_cvt_pk_bf16_f32 v6, v8, v9
	v_cvt_pk_bf16_f32 v7, v10, v11
	ds_write_b128 v40, v[0:3]
	ds_write_b128 v40, v[4:7] offset:128
	s_waitcnt lgkmcnt(0)
	s_barrier
	ds_read_b64_tr_b16 v[44:45], v152 offset:17408
	ds_read_b64_tr_b16 v[46:47], v152 offset:18496
	ds_read_b64_tr_b16 v[60:61], v155 offset:0
	ds_read_b64_tr_b16 v[62:63], v155 offset:1088
	ds_read_b64_tr_b16 v[76:77], v154 offset:0
	ds_read_b64_tr_b16 v[78:79], v154 offset:1088
	ds_read_b64_tr_b16 v[48:49], v152 offset:21760
	ds_read_b64_tr_b16 v[50:51], v152 offset:22848
	ds_read_b64_tr_b16 v[64:65], v155 offset:4352
	ds_read_b64_tr_b16 v[66:67], v155 offset:5440
	ds_read_b64_tr_b16 v[80:81], v154 offset:4352
	ds_read_b64_tr_b16 v[82:83], v154 offset:5440
	ds_read_b64_tr_b16 v[52:53], v152 offset:26112
	ds_read_b64_tr_b16 v[54:55], v152 offset:27200
	ds_read_b64_tr_b16 v[68:69], v155 offset:8704
	ds_read_b64_tr_b16 v[70:71], v155 offset:9792
	ds_read_b64_tr_b16 v[84:85], v154 offset:8704
	ds_read_b64_tr_b16 v[86:87], v154 offset:9792
	ds_read_b64_tr_b16 v[56:57], v152 offset:30464
	ds_read_b64_tr_b16 v[58:59], v152 offset:31552
	ds_read_b64_tr_b16 v[72:73], v155 offset:13056
	ds_read_b64_tr_b16 v[74:75], v155 offset:14144
	ds_read_b64_tr_b16 v[88:89], v154 offset:13056
	ds_read_b64_tr_b16 v[90:91], v154 offset:14144
	s_waitcnt lgkmcnt(0)
	v_mfma_f32_32x32x16_bf16 v[0:15], v[44:47], v[60:63], 0
	v_mfma_f32_32x32x16_bf16 v[16:31], v[44:47], v[76:79], 0
	v_mfma_f32_32x32x16_bf16 v[0:15], v[48:51], v[64:67], v[0:15]
	v_mfma_f32_32x32x16_bf16 v[16:31], v[48:51], v[80:83], v[16:31]
	v_mfma_f32_32x32x16_bf16 v[0:15], v[52:55], v[68:71], v[0:15]
	v_mfma_f32_32x32x16_bf16 v[16:31], v[52:55], v[84:87], v[16:31]
	v_mfma_f32_32x32x16_bf16 v[0:15], v[56:59], v[72:75], v[0:15]
	v_mfma_f32_32x32x16_bf16 v[16:31], v[56:59], v[88:91], v[16:31]
	s_nop 15
	s_nop 3
	v_cvt_pk_bf16_f32 v0, v0, v1
	v_cvt_pk_bf16_f32 v2, v2, v3
	v_cvt_pk_bf16_f32 v4, v4, v5
	v_cvt_pk_bf16_f32 v6, v6, v7
	v_cvt_pk_bf16_f32 v8, v8, v9
	v_cvt_pk_bf16_f32 v10, v10, v11
	v_cvt_pk_bf16_f32 v12, v12, v13
	v_cvt_pk_bf16_f32 v14, v14, v15
	s_nop 4
	v_cvt_pk_bf16_f32 v16, v16, v17
	v_cvt_pk_bf16_f32 v18, v18, v19
	v_cvt_pk_bf16_f32 v20, v20, v21
	v_cvt_pk_bf16_f32 v22, v22, v23
	v_cvt_pk_bf16_f32 v24, v24, v25
	v_cvt_pk_bf16_f32 v26, v26, v27
	v_cvt_pk_bf16_f32 v28, v28, v29
	v_cvt_pk_bf16_f32 v30, v30, v31
	v_mov_b32_dpp v1, v0 quad_perm:[1,0,3,2] row_mask:0xf bank_mask:0xf
	v_mov_b32_dpp v3, v2 quad_perm:[1,0,3,2] row_mask:0xf bank_mask:0xf
	v_mov_b32_dpp v5, v4 quad_perm:[1,0,3,2] row_mask:0xf bank_mask:0xf
	v_mov_b32_dpp v7, v6 quad_perm:[1,0,3,2] row_mask:0xf bank_mask:0xf
	v_mov_b32_dpp v9, v8 quad_perm:[1,0,3,2] row_mask:0xf bank_mask:0xf
	v_mov_b32_dpp v11, v10 quad_perm:[1,0,3,2] row_mask:0xf bank_mask:0xf
	v_mov_b32_dpp v13, v12 quad_perm:[1,0,3,2] row_mask:0xf bank_mask:0xf
	v_mov_b32_dpp v15, v14 quad_perm:[1,0,3,2] row_mask:0xf bank_mask:0xf
	v_mov_b32_dpp v17, v16 quad_perm:[1,0,3,2] row_mask:0xf bank_mask:0xf
	v_mov_b32_dpp v19, v18 quad_perm:[1,0,3,2] row_mask:0xf bank_mask:0xf
	v_mov_b32_dpp v21, v20 quad_perm:[1,0,3,2] row_mask:0xf bank_mask:0xf
	v_mov_b32_dpp v23, v22 quad_perm:[1,0,3,2] row_mask:0xf bank_mask:0xf
	v_mov_b32_dpp v25, v24 quad_perm:[1,0,3,2] row_mask:0xf bank_mask:0xf
	v_mov_b32_dpp v27, v26 quad_perm:[1,0,3,2] row_mask:0xf bank_mask:0xf
	v_mov_b32_dpp v29, v28 quad_perm:[1,0,3,2] row_mask:0xf bank_mask:0xf
	v_mov_b32_dpp v31, v30 quad_perm:[1,0,3,2] row_mask:0xf bank_mask:0xf
	v_perm_b32 v0, v1, v0, v162
	v_perm_b32 v2, v3, v2, v162
	v_perm_b32 v4, v5, v4, v162
	v_perm_b32 v6, v7, v6, v162
	v_perm_b32 v8, v9, v8, v162
	v_perm_b32 v10, v11, v10, v162
	v_perm_b32 v12, v13, v12, v162
	v_perm_b32 v14, v15, v14, v162
	v_perm_b32 v16, v17, v16, v162
	v_perm_b32 v18, v19, v18, v162
	v_perm_b32 v20, v21, v20, v162
	v_perm_b32 v22, v23, v22, v162
	v_perm_b32 v24, v25, v24, v162
	v_perm_b32 v26, v27, v26, v162
	v_perm_b32 v28, v29, v28, v162
	v_perm_b32 v30, v31, v30, v162
	v_lshl_add_u64 v[158:159], v[36:37], 0, v[156:157]
	v_lshl_add_u64 v[160:161], v[34:35], 0, v[156:157]
	global_store_dword v[158:159], v0, off offset:-2880
	global_store_dword v[158:159], v16, off offset:-2816
	global_store_dword v[158:159], v2, off offset:-2368
	global_store_dword v[158:159], v18, off offset:-2304
	global_store_dword v[158:159], v4, off offset:-832
	global_store_dword v[158:159], v20, off offset:-768
	global_store_dword v[158:159], v6, off offset:-320
	global_store_dword v[158:159], v22, off offset:-256
	global_store_dword v[160:161], v8, off offset:-2880
	global_store_dword v[160:161], v24, off offset:-2816
	global_store_dword v[160:161], v10, off offset:-2368
	global_store_dword v[160:161], v26, off offset:-2304
	global_store_dword v[160:161], v12, off offset:-832
	global_store_dword v[160:161], v28, off offset:-768
	global_store_dword v[160:161], v14, off offset:-320
	global_store_dword v[160:161], v30, off offset:-256
	s_waitcnt lgkmcnt(0)
	s_barrier
	v_lshl_add_u64 v[34:35], v[34:35], 0, s[34:35]
	s_cmp_lg_u32 s16, 0
	s_cbranch_scc1 .LBB0_464
